# rwkv_prep sub-pass epilogues: v_rcp instead of IEEE div sequences
# speedup vs baseline: 1.1654x; 1.0078x over previous
.LBB0_519:
	v_readlane_b32 s12, v255, 29
	v_readlane_b32 s20, v255, 37
	v_readlane_b32 s21, v255, 38
	v_readlane_b32 s13, v255, 30
	v_readlane_b32 s14, v255, 31
	v_lshl_add_u64 v[24:25], v[18:19], 2, s[20:21]
	v_readlane_b32 s15, v255, 32
	v_readlane_b32 s16, v255, 33
	v_readlane_b32 s17, v255, 34
	v_readlane_b32 s18, v255, 35
	v_readlane_b32 s19, v255, 36
	v_readlane_b32 s22, v255, 39
	v_readlane_b32 s23, v255, 40
	v_readlane_b32 s24, v255, 41
	v_readlane_b32 s25, v255, 42
	v_readlane_b32 s26, v255, 43
	v_readlane_b32 s27, v255, 44
	s_waitcnt vmcnt(0)
	v_add_f32_e32 v24, v0, v86
	v_mul_f32_e32 v24, 0xbfb8aa3b, v24
	v_exp_f32_e32 v24, v24
	s_nop 0
	v_add_f32_e32 v24, 1.0, v24
	s_nop 0
	v_rcp_f32_e32 v24, v24
	s_nop 0
	v_cvt_pk_bf16_f32 v25, v24, s0
	v_lshl_add_u32 v24, v18, 1, v21
	ds_write_b16 v24, v25 offset:9216
	v_add_f32_e32 v25, v1, v86
	v_mul_f32_e32 v25, 0xbfb8aa3b, v25
	v_exp_f32_e32 v25, v25
	s_nop 0
	v_add_f32_e32 v25, 1.0, v25
	s_nop 0
	v_rcp_f32_e32 v25, v25
	s_nop 0
	v_cvt_pk_bf16_f32 v25, v25, s0
	ds_write_b16 v24, v25 offset:10256
	v_add_f32_e32 v25, v2, v86
	v_mul_f32_e32 v25, 0xbfb8aa3b, v25
	v_exp_f32_e32 v25, v25
	s_nop 0
	v_add_f32_e32 v25, 1.0, v25
	s_nop 0
	v_rcp_f32_e32 v25, v25
	s_nop 0
	v_cvt_pk_bf16_f32 v25, v25, s0
	ds_write_b16 v24, v25 offset:11296
	v_add_f32_e32 v25, v3, v86
	v_mul_f32_e32 v25, 0xbfb8aa3b, v25
	v_exp_f32_e32 v25, v25
	s_nop 0
	v_add_f32_e32 v25, 1.0, v25
	s_nop 0
	v_rcp_f32_e32 v25, v25
	s_nop 0
	v_cvt_pk_bf16_f32 v25, v25, s0
	ds_write_b16 v24, v25 offset:12336
	v_add_f32_e32 v25, v4, v86
	v_mul_f32_e32 v25, 0xbfb8aa3b, v25
	v_exp_f32_e32 v25, v25
	s_nop 0
	v_add_f32_e32 v25, 1.0, v25
	s_nop 0
	v_rcp_f32_e32 v25, v25
	s_nop 0
	v_cvt_pk_bf16_f32 v25, v25, s0
	ds_write_b16 v24, v25 offset:17536
	v_add_f32_e32 v25, v5, v86
	v_mul_f32_e32 v25, 0xbfb8aa3b, v25
	v_exp_f32_e32 v25, v25
	s_nop 0
	v_add_f32_e32 v25, 1.0, v25
	s_nop 0
	v_rcp_f32_e32 v25, v25
	s_nop 0
	v_cvt_pk_bf16_f32 v25, v25, s0
	ds_write_b16 v24, v25 offset:18576
	v_add_f32_e32 v25, v6, v86
	v_mul_f32_e32 v25, 0xbfb8aa3b, v25
	v_exp_f32_e32 v25, v25
	s_nop 0
	v_add_f32_e32 v25, 1.0, v25
	s_nop 0
	v_rcp_f32_e32 v25, v25
	s_nop 0
	v_cvt_pk_bf16_f32 v25, v25, s0
	ds_write_b16 v24, v25 offset:19616
	v_add_f32_e32 v25, v7, v86
	v_mul_f32_e32 v25, 0xbfb8aa3b, v25
	v_exp_f32_e32 v25, v25
	s_nop 0
	v_add_f32_e32 v25, 1.0, v25
	s_nop 0
	v_rcp_f32_e32 v25, v25
	s_nop 0
	v_cvt_pk_bf16_f32 v25, v25, s0
	ds_write_b16 v24, v25 offset:20656
	v_add_f32_e32 v25, v8, v86
	v_mul_f32_e32 v25, 0xbfb8aa3b, v25
	v_exp_f32_e32 v25, v25
	s_nop 0
	v_add_f32_e32 v25, 1.0, v25
	s_nop 0
	v_rcp_f32_e32 v25, v25
	s_nop 0
	v_cvt_pk_bf16_f32 v25, v25, s0
	ds_write_b16 v24, v25 offset:25856
	v_add_f32_e32 v25, v9, v86
	v_mul_f32_e32 v25, 0xbfb8aa3b, v25
	v_exp_f32_e32 v25, v25
	s_nop 0
	v_add_f32_e32 v25, 1.0, v25
	s_nop 0
	v_rcp_f32_e32 v25, v25
	s_nop 0
	v_cvt_pk_bf16_f32 v25, v25, s0
	ds_write_b16 v24, v25 offset:26896
	v_add_f32_e32 v25, v10, v86
	v_mul_f32_e32 v25, 0xbfb8aa3b, v25
	v_exp_f32_e32 v25, v25
	s_nop 0
	v_add_f32_e32 v25, 1.0, v25
	s_nop 0
	v_rcp_f32_e32 v25, v25
	s_nop 0
	v_cvt_pk_bf16_f32 v25, v25, s0
	ds_write_b16 v24, v25 offset:27936
	v_add_f32_e32 v25, v11, v86
	v_mul_f32_e32 v25, 0xbfb8aa3b, v25
	v_exp_f32_e32 v25, v25
	s_nop 0
	v_add_f32_e32 v25, 1.0, v25
	s_nop 0
	v_rcp_f32_e32 v25, v25
	s_nop 0
	v_cvt_pk_bf16_f32 v25, v25, s0
	ds_write_b16 v24, v25 offset:28976
	v_add_f32_e32 v25, v12, v86
	v_mul_f32_e32 v25, 0xbfb8aa3b, v25
	v_exp_f32_e32 v25, v25
	s_nop 0
	v_add_f32_e32 v25, 1.0, v25
	s_nop 0
	v_rcp_f32_e32 v25, v25
	s_nop 0
	v_cvt_pk_bf16_f32 v25, v25, s0
	ds_write_b16 v24, v25 offset:34176
	v_add_f32_e32 v25, v13, v86
	v_mul_f32_e32 v25, 0xbfb8aa3b, v25
	v_exp_f32_e32 v25, v25
	s_nop 0
	v_add_f32_e32 v25, 1.0, v25
	s_nop 0
	v_rcp_f32_e32 v25, v25
	s_nop 0
	v_cvt_pk_bf16_f32 v25, v25, s0
	ds_write_b16 v24, v25 offset:35216
	v_add_f32_e32 v25, v14, v86
	v_mul_f32_e32 v25, 0xbfb8aa3b, v25
	v_exp_f32_e32 v25, v25
	v_add_f32_e32 v23, v15, v86
	v_mul_f32_e32 v23, 0xbfb8aa3b, v23
	v_exp_f32_e32 v23, v23
	v_add_f32_e32 v25, 1.0, v25
	v_add_f32_e32 v23, 1.0, v23
	v_rcp_f32_e32 v25, v25
	s_nop 0
	v_cvt_pk_bf16_f32 v25, v25, s0
	ds_write_b16 v24, v25 offset:36256
	s_nop 0
	v_rcp_f32_e32 v23, v23
	s_nop 0
	v_cvt_pk_bf16_f32 v23, v23, s0
	ds_write_b16 v24, v23 offset:37296
	s_cbranch_execnz .LBB0_516
.LBB0_520:
	v_readlane_b32 s12, v255, 29
	v_lshlrev_b64 v[18:19], 2, v[18:19]
	v_readlane_b32 s16, v255, 33
	v_readlane_b32 s17, v255, 34
	v_readlane_b32 s13, v255, 30
	v_readlane_b32 s14, v255, 31
	v_lshl_add_u64 v[24:25], s[16:17], 0, v[18:19]
	v_lshl_add_u64 v[18:19], v[16:17], 0, v[18:19]
	v_readlane_b32 s15, v255, 32
	v_readlane_b32 s18, v255, 35
	v_readlane_b32 s19, v255, 36
	v_readlane_b32 s20, v255, 37
	v_readlane_b32 s21, v255, 38
	v_readlane_b32 s22, v255, 39
	v_readlane_b32 s23, v255, 40
	v_readlane_b32 s24, v255, 41
	v_readlane_b32 s25, v255, 42
	v_readlane_b32 s26, v255, 43
	v_readlane_b32 s27, v255, 44
	s_waitcnt vmcnt(0)
	v_add_f32_e32 v0, v0, v86
	v_mul_f32_e32 v0, 0xbfb8aa3b, v0
	v_exp_f32_e32 v0, v0
	s_nop 0
	v_add_f32_e32 v0, 1.0, v0
	s_nop 0
	v_rcp_f32_e32 v0, v0
	s_nop 0
	v_mul_f32_e32 v0, 0xbf1b4598, v0
	v_mul_f32_e32 v0, 0x3fb8aa3b, v0
	v_exp_f32_e32 v0, v0
	global_store_dword v[18:19], v0, off nt
	v_add_f32_e32 v0, v1, v86
	v_mul_f32_e32 v0, 0xbfb8aa3b, v0
	v_exp_f32_e32 v0, v0
	s_nop 0
	v_add_f32_e32 v0, 1.0, v0
	s_nop 0
	v_rcp_f32_e32 v0, v0
	s_nop 0
	v_mul_f32_e32 v0, 0xbf1b4598, v0
	v_mul_f32_e32 v0, 0x3fb8aa3b, v0
	v_exp_f32_e32 v0, v0
	global_store_dword v[18:19], v0, off offset:2048 nt
	v_add_f32_e32 v0, v2, v86
	v_mul_f32_e32 v0, 0xbfb8aa3b, v0
	v_exp_f32_e32 v0, v0
	s_nop 0
	v_add_f32_e32 v0, 1.0, v0
	s_movk_i32 s4, 0x1000
	v_rcp_f32_e32 v0, v0
	s_nop 0
	v_mul_f32_e32 v0, 0xbf1b4598, v0
	v_mul_f32_e32 v0, 0x3fb8aa3b, v0
	v_exp_f32_e32 v2, v0
	v_add_co_u32_e32 v0, vcc, s4, v18
	s_nop 1
	v_addc_co_u32_e32 v1, vcc, 0, v19, vcc
	global_store_dword v[0:1], v2, off nt
	v_add_f32_e32 v2, v3, v86
	v_mul_f32_e32 v2, 0xbfb8aa3b, v2
	v_exp_f32_e32 v2, v2
	s_nop 0
	v_add_f32_e32 v2, 1.0, v2
	s_nop 0
	v_rcp_f32_e32 v2, v2
	s_nop 0
	v_mul_f32_e32 v2, 0xbf1b4598, v2
	v_mul_f32_e32 v2, 0x3fb8aa3b, v2
	v_exp_f32_e32 v2, v2
	global_store_dword v[0:1], v2, off offset:2048 nt
	v_add_f32_e32 v0, v4, v86
	v_mul_f32_e32 v0, 0xbfb8aa3b, v0
	v_exp_f32_e32 v0, v0
	s_nop 0
	v_add_f32_e32 v0, 1.0, v0
	s_movk_i32 s4, 0x4000
	v_rcp_f32_e32 v0, v0
	s_nop 0
	v_mul_f32_e32 v0, 0xbf1b4598, v0
	v_mul_f32_e32 v0, 0x3fb8aa3b, v0
	v_exp_f32_e32 v4, v0
	v_add_co_u32_e32 v0, vcc, s4, v18
	s_movk_i32 s4, 0x5000
	s_nop 0
	v_addc_co_u32_e32 v1, vcc, 0, v19, vcc
	v_add_co_u32_e32 v2, vcc, s4, v18
	s_nop 1
	v_addc_co_u32_e32 v3, vcc, 0, v19, vcc
	global_store_dword v[2:3], v4, off offset:-4096 nt
	v_add_f32_e32 v4, v5, v86
	v_mul_f32_e32 v4, 0xbfb8aa3b, v4
	v_exp_f32_e32 v4, v4
	s_nop 0
	v_add_f32_e32 v4, 1.0, v4
	s_nop 0
	v_rcp_f32_e32 v4, v4
	s_nop 0
	v_mul_f32_e32 v4, 0xbf1b4598, v4
	v_mul_f32_e32 v4, 0x3fb8aa3b, v4
	v_exp_f32_e32 v4, v4
	global_store_dword v[0:1], v4, off offset:2048 nt
	v_add_f32_e32 v0, v6, v86
	v_mul_f32_e32 v0, 0xbfb8aa3b, v0
	v_exp_f32_e32 v0, v0
	s_nop 0
	v_add_f32_e32 v0, 1.0, v0
	s_nop 0
	v_rcp_f32_e32 v0, v0
	s_nop 0
	v_mul_f32_e32 v0, 0xbf1b4598, v0
	v_mul_f32_e32 v0, 0x3fb8aa3b, v0
	v_exp_f32_e32 v0, v0
	global_store_dword v[2:3], v0, off nt
	v_add_f32_e32 v0, v7, v86
	v_mul_f32_e32 v0, 0xbfb8aa3b, v0
	v_exp_f32_e32 v0, v0
	s_nop 0
	v_add_f32_e32 v0, 1.0, v0
	s_nop 0
	v_rcp_f32_e32 v0, v0
	s_nop 0
	v_mul_f32_e32 v0, 0xbf1b4598, v0
	v_mul_f32_e32 v0, 0x3fb8aa3b, v0
	v_exp_f32_e32 v0, v0
	global_store_dword v[2:3], v0, off offset:2048 nt
	v_add_f32_e32 v0, v8, v86
	v_mul_f32_e32 v0, 0xbfb8aa3b, v0
	v_exp_f32_e32 v0, v0
	s_nop 0
	v_add_f32_e32 v0, 1.0, v0
	s_mov_b32 s4, 0x8000
	v_rcp_f32_e32 v0, v0
	s_nop 0
	v_mul_f32_e32 v0, 0xbf1b4598, v0
	v_mul_f32_e32 v0, 0x3fb8aa3b, v0
	v_exp_f32_e32 v4, v0
	v_add_co_u32_e32 v0, vcc, s4, v18
	s_mov_b32 s4, 0x9000
	s_nop 0
	v_addc_co_u32_e32 v1, vcc, 0, v19, vcc
	v_add_co_u32_e32 v2, vcc, s4, v18
	s_nop 1
	v_addc_co_u32_e32 v3, vcc, 0, v19, vcc
	global_store_dword v[2:3], v4, off offset:-4096 nt
	v_add_f32_e32 v4, v9, v86
	v_mul_f32_e32 v4, 0xbfb8aa3b, v4
	v_exp_f32_e32 v4, v4
	s_nop 0
	v_add_f32_e32 v4, 1.0, v4
	s_nop 0
	v_rcp_f32_e32 v4, v4
	s_nop 0
	v_mul_f32_e32 v4, 0xbf1b4598, v4
	v_mul_f32_e32 v4, 0x3fb8aa3b, v4
	v_exp_f32_e32 v4, v4
	global_store_dword v[0:1], v4, off offset:2048 nt
	v_add_f32_e32 v0, v10, v86
	v_mul_f32_e32 v0, 0xbfb8aa3b, v0
	v_exp_f32_e32 v0, v0
	s_nop 0
	v_add_f32_e32 v0, 1.0, v0
	s_nop 0
	v_rcp_f32_e32 v0, v0
	s_nop 0
	v_mul_f32_e32 v0, 0xbf1b4598, v0
	v_mul_f32_e32 v0, 0x3fb8aa3b, v0
	v_exp_f32_e32 v0, v0
	global_store_dword v[2:3], v0, off nt
	v_add_f32_e32 v0, v11, v86
	v_mul_f32_e32 v0, 0xbfb8aa3b, v0
	v_exp_f32_e32 v0, v0
	s_nop 0
	v_add_f32_e32 v0, 1.0, v0
	s_nop 0
	v_rcp_f32_e32 v0, v0
	s_nop 0
	v_mul_f32_e32 v0, 0xbf1b4598, v0
	v_mul_f32_e32 v0, 0x3fb8aa3b, v0
	v_exp_f32_e32 v0, v0
	global_store_dword v[2:3], v0, off offset:2048 nt
	v_add_f32_e32 v0, v12, v86
	v_mul_f32_e32 v0, 0xbfb8aa3b, v0
	v_exp_f32_e32 v0, v0
	s_nop 0
	v_add_f32_e32 v0, 1.0, v0
	s_mov_b32 s4, 0xc000
	v_rcp_f32_e32 v0, v0
	s_nop 0
	v_mul_f32_e32 v0, 0xbf1b4598, v0
	v_mul_f32_e32 v0, 0x3fb8aa3b, v0
	v_exp_f32_e32 v4, v0
	v_add_co_u32_e32 v0, vcc, s4, v18
	s_mov_b32 s4, 0xd000
	s_nop 0
	v_addc_co_u32_e32 v1, vcc, 0, v19, vcc
	v_add_co_u32_e32 v2, vcc, s4, v18
	s_nop 1
	v_addc_co_u32_e32 v3, vcc, 0, v19, vcc
	global_store_dword v[2:3], v4, off offset:-4096 nt
	v_add_f32_e32 v4, v13, v86
	v_mul_f32_e32 v4, 0xbfb8aa3b, v4
	v_exp_f32_e32 v4, v4
	s_nop 0
	v_add_f32_e32 v4, 1.0, v4
	s_nop 0
	v_rcp_f32_e32 v4, v4
	s_nop 0
	v_mul_f32_e32 v4, 0xbf1b4598, v4
	v_mul_f32_e32 v4, 0x3fb8aa3b, v4
	v_exp_f32_e32 v4, v4
	global_store_dword v[0:1], v4, off offset:2048 nt
	v_add_f32_e32 v0, v14, v86
	v_mul_f32_e32 v0, 0xbfb8aa3b, v0
	v_exp_f32_e32 v0, v0
	s_nop 0
	v_add_f32_e32 v0, 1.0, v0
	s_nop 0
	v_rcp_f32_e32 v0, v0
	s_nop 0
	v_mul_f32_e32 v0, 0xbf1b4598, v0
	v_mul_f32_e32 v0, 0x3fb8aa3b, v0
	v_exp_f32_e32 v0, v0
	global_store_dword v[2:3], v0, off nt
	v_add_f32_e32 v0, v15, v86
	v_mul_f32_e32 v0, 0xbfb8aa3b, v0
	v_exp_f32_e32 v0, v0
	s_nop 0
	v_add_f32_e32 v0, 1.0, v0
	s_nop 0
	v_rcp_f32_e32 v0, v0
	s_nop 0
	v_mul_f32_e32 v0, 0xbf1b4598, v0
	v_mul_f32_e32 v0, 0x3fb8aa3b, v0
	v_exp_f32_e32 v0, v0
	global_store_dword v[2:3], v0, off offset:2048 nt
	s_branch .LBB0_516
